# v18 + s5_stage2 Kd loop software-pipelined: 3 batches of 8 taps in flight across outputs (same per-tap arithmetic and order)
# speedup vs baseline: 1.0026x; 1.0003x over previous
; __device__ void s5_stage2(const Params& p, int l) {
;     ...
;     for (int o = t0; o < 524288; o += gs) {
;         const int c2 = o & 15, c = (o >> 4) & 15, k = (o >> 8) & 15, dg = o >> 12;
;         float acc = 0.f;
;         for (int p0 = 0; p0 < 64; p0 += 8) {
;             float2 A[8], Bb[8]; float Cr[8], Ci[8];
; #pragma unroll
;             for (int q = 0; q < 8; ++q) { const int sidx = dg * 64 + p0 + q; A[q] = Apow[sidx * 18 + k]; Bb[q] = Bbar[sidx * 16 + c2]; Cr[q] = cre[(dg * 16 + c) * 64 + p0 + q]; Ci[q] = cim[(dg * 16 + c) * 64 + p0 + q]; }
;             asm volatile("" ::: "memory");
; #pragma unroll
;             for (int q = 0; q < 8; ++q) { const float abr = A[q].x * Bb[q].x - A[q].y * Bb[q].y, abi = A[q].x * Bb[q].y + A[q].y * Bb[q].x; acc += Cr[q] * abr - Ci[q] * abi; }
;         }
;         Kd[o] = acc;
;     }
.LBB0_773:
	v_lshrrev_b32_e32 v28, 12, v14
	v_bfe_u32 v29, v14, 8, 4
	v_mul_u32_u24_e32 v16, 0x2400, v28
	v_lshl_add_u32 v16, v29, 3, v16
	v_add_u32_e32 v17, 0xfc0, v16
	v_add_u32_e32 v18, 0x1f80, v16
	v_lshlrev_b32_e32 v19, 13, v28
	v_lshl_or_b32 v19, v41, 3, v19
	v_add_u32_e32 v20, 0x1000, v19
	v_bfe_u32 v29, v14, 4, 4
	v_lshlrev_b32_e32 v21, 12, v28
	v_lshl_or_b32 v21, v29, 8, v21
	v_readlane_b32 s2, v252, 21
	v_readlane_b32 s3, v252, 22
	global_load_dwordx2 v[160:161], v16, s[30:31] offset:2304
	global_load_dwordx2 v[176:177], v19, s[8:9] offset:2048
	global_load_dwordx2 v[162:163], v16, s[30:31] offset:2448
	global_load_dwordx2 v[178:179], v19, s[8:9] offset:2176
	global_load_dwordx2 v[164:165], v16, s[30:31] offset:2592
	global_load_dwordx2 v[180:181], v19, s[8:9] offset:2304
	global_load_dwordx2 v[166:167], v16, s[30:31] offset:2736
	global_load_dwordx2 v[182:183], v19, s[8:9] offset:2432
	global_load_dwordx2 v[168:169], v16, s[30:31] offset:2880
	global_load_dwordx2 v[184:185], v19, s[8:9] offset:2560
	global_load_dwordx2 v[170:171], v16, s[30:31] offset:3024
	global_load_dwordx2 v[186:187], v19, s[8:9] offset:2688
	global_load_dwordx2 v[172:173], v16, s[30:31] offset:3168
	global_load_dwordx2 v[188:189], v19, s[8:9] offset:2816
	global_load_dwordx2 v[174:175], v16, s[30:31] offset:3312
	global_load_dwordx2 v[190:191], v19, s[8:9] offset:2944
	global_load_dwordx4 v[196:199], v21, s[26:27] offset:64
	global_load_dwordx4 v[200:203], v21, s[26:27] offset:80
	global_load_dwordx4 v[204:207], v21, s[40:41] offset:64
	global_load_dwordx4 v[208:211], v21, s[40:41] offset:80
	global_load_dwordx2 v[64:65], v16, s[30:31]
	global_load_dwordx2 v[80:81], v19, s[8:9]
	global_load_dwordx2 v[66:67], v16, s[30:31] offset:144
	global_load_dwordx2 v[82:83], v19, s[8:9] offset:128
	global_load_dwordx2 v[68:69], v16, s[30:31] offset:288
	global_load_dwordx2 v[84:85], v19, s[8:9] offset:256
	global_load_dwordx2 v[70:71], v16, s[30:31] offset:432
	global_load_dwordx2 v[86:87], v19, s[8:9] offset:384
	global_load_dwordx2 v[72:73], v16, s[30:31] offset:576
	global_load_dwordx2 v[88:89], v19, s[8:9] offset:512
	global_load_dwordx2 v[74:75], v16, s[30:31] offset:720
	global_load_dwordx2 v[90:91], v19, s[8:9] offset:640
	global_load_dwordx2 v[76:77], v16, s[30:31] offset:864
	global_load_dwordx2 v[92:93], v19, s[8:9] offset:768
	global_load_dwordx2 v[78:79], v16, s[30:31] offset:1008
	global_load_dwordx2 v[94:95], v19, s[8:9] offset:896
	global_load_dwordx4 v[96:99], v21, s[26:27]
	global_load_dwordx4 v[100:103], v21, s[26:27] offset:16
	global_load_dwordx4 v[104:107], v21, s[40:41]
	global_load_dwordx4 v[108:111], v21, s[40:41] offset:16
	global_load_dwordx2 v[112:113], v16, s[30:31] offset:1152
	global_load_dwordx2 v[128:129], v19, s[8:9] offset:1024
	global_load_dwordx2 v[114:115], v16, s[30:31] offset:1296
	global_load_dwordx2 v[130:131], v19, s[8:9] offset:1152
	global_load_dwordx2 v[116:117], v16, s[30:31] offset:1440
	global_load_dwordx2 v[132:133], v19, s[8:9] offset:1280
	global_load_dwordx2 v[118:119], v16, s[30:31] offset:1584
	global_load_dwordx2 v[134:135], v19, s[8:9] offset:1408
	global_load_dwordx2 v[120:121], v16, s[30:31] offset:1728
	global_load_dwordx2 v[136:137], v19, s[8:9] offset:1536
	global_load_dwordx2 v[122:123], v16, s[30:31] offset:1872
	global_load_dwordx2 v[138:139], v19, s[8:9] offset:1664
	global_load_dwordx2 v[124:125], v16, s[30:31] offset:2016
	global_load_dwordx2 v[140:141], v19, s[8:9] offset:1792
	global_load_dwordx2 v[126:127], v16, s[30:31] offset:2160
	global_load_dwordx2 v[142:143], v19, s[8:9] offset:1920
	global_load_dwordx4 v[144:147], v21, s[26:27] offset:32
	global_load_dwordx4 v[148:151], v21, s[26:27] offset:48
	global_load_dwordx4 v[152:155], v21, s[40:41] offset:32
	global_load_dwordx4 v[156:159], v21, s[40:41] offset:48
	global_load_dword v37, v21, s[26:27]
.Lst2_loop:
	v_add_u32_e32 v15, s6, v14
	s_nop 0
	v_readfirstlane_b32 s1, v15
	s_cmp_lt_i32 s1, 0x80000
	s_cselect_b64 s[38:39], -1, 0
	s_cselect_b64 vcc, -1, 0
	v_cndmask_b32_e32 v13, v14, v15, vcc
	v_lshrrev_b32_e32 v28, 12, v13
	v_bfe_u32 v29, v13, 8, 4
	v_mul_u32_u24_e32 v22, 0x2400, v28
	v_lshl_add_u32 v22, v29, 3, v22
	v_add_u32_e32 v23, 0xfc0, v22
	v_add_u32_e32 v24, 0x1f80, v22
	v_lshlrev_b32_e32 v25, 13, v28
	v_lshl_or_b32 v25, v41, 3, v25
	v_add_u32_e32 v26, 0x1000, v25
	v_bfe_u32 v29, v13, 4, 4
	v_lshlrev_b32_e32 v27, 12, v28
	v_lshl_or_b32 v27, v29, 8, v27
	s_waitcnt vmcnt(21)
; __device__ void s5_stage2(const Params& p, int l) {
;     ...
;     for (int o = t0; o < 524288; o += gs) {
;         const int c2 = o & 15, c = (o >> 4) & 15, k = (o >> 8) & 15, dg = o >> 12;
;         float acc = 0.f;
;         for (int p0 = 0; p0 < 64; p0 += 8) {
;             float2 A[8], Bb[8]; float Cr[8], Ci[8];
; #pragma unroll
;             for (int q = 0; q < 8; ++q) { const int sidx = dg * 64 + p0 + q; A[q] = Apow[sidx * 18 + k]; Bb[q] = Bbar[sidx * 16 + c2]; Cr[q] = cre[(dg * 16 + c) * 64 + p0 + q]; Ci[q] = cim[(dg * 16 + c) * 64 + p0 + q]; }
;             asm volatile("" ::: "memory");
; #pragma unroll
;             for (int q = 0; q < 8; ++q) { const float abr = A[q].x * Bb[q].x - A[q].y * Bb[q].y, abi = A[q].x * Bb[q].y + A[q].y * Bb[q].x; acc += Cr[q] * abr - Ci[q] * abi; }
;         }
;         Kd[o] = acc;
;     }
	v_mul_f32_e32 v34, v64, v81
	v_mul_f32_e32 v33, v65, v81
	v_fmac_f32_e32 v34, v65, v80
	v_fma_f32 v33, v64, v80, -v33
	v_mul_f32_e32 v34, v104, v34
	v_fma_f32 v33, v96, v33, -v34
	v_add_f32_e32 v32, 0, v33
	v_mul_f32_e32 v36, v66, v83
	v_mul_f32_e32 v35, v67, v83
	v_fmac_f32_e32 v36, v67, v82
	v_fma_f32 v35, v66, v82, -v35
	v_mul_f32_e32 v36, v105, v36
	v_fma_f32 v35, v97, v35, -v36
	v_add_f32_e32 v32, v32, v35
	v_mul_f32_e32 v34, v68, v85
	v_mul_f32_e32 v33, v69, v85
	v_fmac_f32_e32 v34, v69, v84
	v_fma_f32 v33, v68, v84, -v33
	v_mul_f32_e32 v34, v106, v34
	v_fma_f32 v33, v98, v33, -v34
	v_add_f32_e32 v32, v32, v33
	v_mul_f32_e32 v36, v70, v87
	v_mul_f32_e32 v35, v71, v87
	v_fmac_f32_e32 v36, v71, v86
	v_fma_f32 v35, v70, v86, -v35
	v_mul_f32_e32 v36, v107, v36
	v_fma_f32 v35, v99, v35, -v36
	v_add_f32_e32 v32, v32, v35
	v_mul_f32_e32 v34, v72, v89
	v_mul_f32_e32 v33, v73, v89
	v_fmac_f32_e32 v34, v73, v88
	v_fma_f32 v33, v72, v88, -v33
	v_mul_f32_e32 v34, v108, v34
	v_fma_f32 v33, v100, v33, -v34
	v_add_f32_e32 v32, v32, v33
	v_mul_f32_e32 v36, v74, v91
	v_mul_f32_e32 v35, v75, v91
	v_fmac_f32_e32 v36, v75, v90
	v_fma_f32 v35, v74, v90, -v35
	v_mul_f32_e32 v36, v109, v36
	v_fma_f32 v35, v101, v35, -v36
	v_add_f32_e32 v32, v32, v35
	v_mul_f32_e32 v34, v76, v93
	v_mul_f32_e32 v33, v77, v93
	v_fmac_f32_e32 v34, v77, v92
	v_fma_f32 v33, v76, v92, -v33
	v_mul_f32_e32 v34, v110, v34
	v_fma_f32 v33, v102, v33, -v34
	v_add_f32_e32 v32, v32, v33
	v_mul_f32_e32 v36, v78, v95
	v_mul_f32_e32 v35, v79, v95
	v_fmac_f32_e32 v36, v79, v94
	v_fma_f32 v35, v78, v94, -v35
	v_mul_f32_e32 v36, v111, v36
	v_fma_f32 v35, v103, v35, -v36
	v_add_f32_e32 v32, v32, v35
	global_load_dwordx2 v[64:65], v16, s[30:31] offset:3456
	global_load_dwordx2 v[80:81], v19, s[8:9] offset:3072
	global_load_dwordx2 v[66:67], v16, s[30:31] offset:3600
	global_load_dwordx2 v[82:83], v19, s[8:9] offset:3200
	global_load_dwordx2 v[68:69], v16, s[30:31] offset:3744
	global_load_dwordx2 v[84:85], v19, s[8:9] offset:3328
	global_load_dwordx2 v[70:71], v16, s[30:31] offset:3888
	global_load_dwordx2 v[86:87], v19, s[8:9] offset:3456
	global_load_dwordx2 v[72:73], v17, s[30:31]
	global_load_dwordx2 v[88:89], v19, s[8:9] offset:3584
	global_load_dwordx2 v[74:75], v17, s[30:31] offset:144
	global_load_dwordx2 v[90:91], v19, s[8:9] offset:3712
	global_load_dwordx2 v[76:77], v17, s[30:31] offset:288
	global_load_dwordx2 v[92:93], v19, s[8:9] offset:3840
	global_load_dwordx2 v[78:79], v17, s[30:31] offset:432
	global_load_dwordx2 v[94:95], v19, s[8:9] offset:3968
	global_load_dwordx4 v[96:99], v21, s[26:27] offset:96
	global_load_dwordx4 v[100:103], v21, s[26:27] offset:112
	global_load_dwordx4 v[104:107], v21, s[40:41] offset:96
	global_load_dwordx4 v[108:111], v21, s[40:41] offset:112
	s_waitcnt vmcnt(21)
	v_mul_f32_e32 v34, v112, v129
	v_mul_f32_e32 v33, v113, v129
	v_fmac_f32_e32 v34, v113, v128
	v_fma_f32 v33, v112, v128, -v33
	v_mul_f32_e32 v34, v152, v34
	v_fma_f32 v33, v144, v33, -v34
	v_add_f32_e32 v32, v32, v33
	v_mul_f32_e32 v36, v114, v131
	v_mul_f32_e32 v35, v115, v131
	v_fmac_f32_e32 v36, v115, v130
	v_fma_f32 v35, v114, v130, -v35
	v_mul_f32_e32 v36, v153, v36
	v_fma_f32 v35, v145, v35, -v36
	v_add_f32_e32 v32, v32, v35
	v_mul_f32_e32 v34, v116, v133
	v_mul_f32_e32 v33, v117, v133
	v_fmac_f32_e32 v34, v117, v132
	v_fma_f32 v33, v116, v132, -v33
	v_mul_f32_e32 v34, v154, v34
	v_fma_f32 v33, v146, v33, -v34
	v_add_f32_e32 v32, v32, v33
	v_mul_f32_e32 v36, v118, v135
	v_mul_f32_e32 v35, v119, v135
	v_fmac_f32_e32 v36, v119, v134
	v_fma_f32 v35, v118, v134, -v35
	v_mul_f32_e32 v36, v155, v36
	v_fma_f32 v35, v147, v35, -v36
	v_add_f32_e32 v32, v32, v35
	v_mul_f32_e32 v34, v120, v137
	v_mul_f32_e32 v33, v121, v137
	v_fmac_f32_e32 v34, v121, v136
	v_fma_f32 v33, v120, v136, -v33
	v_mul_f32_e32 v34, v156, v34
	v_fma_f32 v33, v148, v33, -v34
	v_add_f32_e32 v32, v32, v33
	v_mul_f32_e32 v36, v122, v139
	v_mul_f32_e32 v35, v123, v139
	v_fmac_f32_e32 v36, v123, v138
	v_fma_f32 v35, v122, v138, -v35
	v_mul_f32_e32 v36, v157, v36
	v_fma_f32 v35, v149, v35, -v36
	v_add_f32_e32 v32, v32, v35
	v_mul_f32_e32 v34, v124, v141
	v_mul_f32_e32 v33, v125, v141
	v_fmac_f32_e32 v34, v125, v140
	v_fma_f32 v33, v124, v140, -v33
	v_mul_f32_e32 v34, v158, v34
	v_fma_f32 v33, v150, v33, -v34
	v_add_f32_e32 v32, v32, v33
	v_mul_f32_e32 v36, v126, v143
	v_mul_f32_e32 v35, v127, v143
	v_fmac_f32_e32 v36, v127, v142
	v_fma_f32 v35, v126, v142, -v35
	v_mul_f32_e32 v36, v159, v36
	v_fma_f32 v35, v151, v35, -v36
	v_add_f32_e32 v32, v32, v35
	global_load_dwordx2 v[112:113], v17, s[30:31] offset:576
	global_load_dwordx2 v[128:129], v20, s[8:9]
	global_load_dwordx2 v[114:115], v17, s[30:31] offset:720
	global_load_dwordx2 v[130:131], v20, s[8:9] offset:128
	global_load_dwordx2 v[116:117], v17, s[30:31] offset:864
	global_load_dwordx2 v[132:133], v20, s[8:9] offset:256
	global_load_dwordx2 v[118:119], v17, s[30:31] offset:1008
	global_load_dwordx2 v[134:135], v20, s[8:9] offset:384
	global_load_dwordx2 v[120:121], v17, s[30:31] offset:1152
	global_load_dwordx2 v[136:137], v20, s[8:9] offset:512
	global_load_dwordx2 v[122:123], v17, s[30:31] offset:1296
	global_load_dwordx2 v[138:139], v20, s[8:9] offset:640
	global_load_dwordx2 v[124:125], v17, s[30:31] offset:1440
	global_load_dwordx2 v[140:141], v20, s[8:9] offset:768
	global_load_dwordx2 v[126:127], v17, s[30:31] offset:1584
	global_load_dwordx2 v[142:143], v20, s[8:9] offset:896
	global_load_dwordx4 v[144:147], v21, s[26:27] offset:128
	global_load_dwordx4 v[148:151], v21, s[26:27] offset:144
	global_load_dwordx4 v[152:155], v21, s[40:41] offset:128
	global_load_dwordx4 v[156:159], v21, s[40:41] offset:144
	s_waitcnt vmcnt(41)
; __device__ void s5_stage2(const Params& p, int l) {
;     ...
;     for (int o = t0; o < 524288; o += gs) {
;         const int c2 = o & 15, c = (o >> 4) & 15, k = (o >> 8) & 15, dg = o >> 12;
;         float acc = 0.f;
;         for (int p0 = 0; p0 < 64; p0 += 8) {
;             float2 A[8], Bb[8]; float Cr[8], Ci[8];
; #pragma unroll
;             for (int q = 0; q < 8; ++q) { const int sidx = dg * 64 + p0 + q; A[q] = Apow[sidx * 18 + k]; Bb[q] = Bbar[sidx * 16 + c2]; Cr[q] = cre[(dg * 16 + c) * 64 + p0 + q]; Ci[q] = cim[(dg * 16 + c) * 64 + p0 + q]; }
;             asm volatile("" ::: "memory");
; #pragma unroll
;             for (int q = 0; q < 8; ++q) { const float abr = A[q].x * Bb[q].x - A[q].y * Bb[q].y, abi = A[q].x * Bb[q].y + A[q].y * Bb[q].x; acc += Cr[q] * abr - Ci[q] * abi; }
;         }
;         Kd[o] = acc;
;     }
	v_mul_f32_e32 v34, v160, v177
	v_mul_f32_e32 v33, v161, v177
	v_fmac_f32_e32 v34, v161, v176
	v_fma_f32 v33, v160, v176, -v33
	v_mul_f32_e32 v34, v204, v34
	v_fma_f32 v33, v196, v33, -v34
	v_add_f32_e32 v32, v32, v33
	v_mul_f32_e32 v36, v162, v179
	v_mul_f32_e32 v35, v163, v179
	v_fmac_f32_e32 v36, v163, v178
	v_fma_f32 v35, v162, v178, -v35
	v_mul_f32_e32 v36, v205, v36
	v_fma_f32 v35, v197, v35, -v36
	v_add_f32_e32 v32, v32, v35
	v_mul_f32_e32 v34, v164, v181
	v_mul_f32_e32 v33, v165, v181
	v_fmac_f32_e32 v34, v165, v180
	v_fma_f32 v33, v164, v180, -v33
	v_mul_f32_e32 v34, v206, v34
	v_fma_f32 v33, v198, v33, -v34
	v_add_f32_e32 v32, v32, v33
	v_mul_f32_e32 v36, v166, v183
	v_mul_f32_e32 v35, v167, v183
	v_fmac_f32_e32 v36, v167, v182
	v_fma_f32 v35, v166, v182, -v35
	v_mul_f32_e32 v36, v207, v36
	v_fma_f32 v35, v199, v35, -v36
	v_add_f32_e32 v32, v32, v35
	v_mul_f32_e32 v34, v168, v185
	v_mul_f32_e32 v33, v169, v185
	v_fmac_f32_e32 v34, v169, v184
	v_fma_f32 v33, v168, v184, -v33
	v_mul_f32_e32 v34, v208, v34
	v_fma_f32 v33, v200, v33, -v34
	v_add_f32_e32 v32, v32, v33
	v_mul_f32_e32 v36, v170, v187
	v_mul_f32_e32 v35, v171, v187
	v_fmac_f32_e32 v36, v171, v186
	v_fma_f32 v35, v170, v186, -v35
	v_mul_f32_e32 v36, v209, v36
	v_fma_f32 v35, v201, v35, -v36
	v_add_f32_e32 v32, v32, v35
	v_mul_f32_e32 v34, v172, v189
	v_mul_f32_e32 v33, v173, v189
	v_fmac_f32_e32 v34, v173, v188
	v_fma_f32 v33, v172, v188, -v33
	v_mul_f32_e32 v34, v210, v34
	v_fma_f32 v33, v202, v33, -v34
	v_add_f32_e32 v32, v32, v33
	v_mul_f32_e32 v36, v174, v191
	v_mul_f32_e32 v35, v175, v191
	v_fmac_f32_e32 v36, v175, v190
	v_fma_f32 v35, v174, v190, -v35
	v_mul_f32_e32 v36, v211, v36
	v_fma_f32 v35, v203, v35, -v36
	v_add_f32_e32 v32, v32, v35
	global_load_dwordx2 v[160:161], v17, s[30:31] offset:1728
	global_load_dwordx2 v[176:177], v20, s[8:9] offset:1024
	global_load_dwordx2 v[162:163], v17, s[30:31] offset:1872
	global_load_dwordx2 v[178:179], v20, s[8:9] offset:1152
	global_load_dwordx2 v[164:165], v17, s[30:31] offset:2016
	global_load_dwordx2 v[180:181], v20, s[8:9] offset:1280
	global_load_dwordx2 v[166:167], v17, s[30:31] offset:2160
	global_load_dwordx2 v[182:183], v20, s[8:9] offset:1408
	global_load_dwordx2 v[168:169], v17, s[30:31] offset:2304
	global_load_dwordx2 v[184:185], v20, s[8:9] offset:1536
	global_load_dwordx2 v[170:171], v17, s[30:31] offset:2448
	global_load_dwordx2 v[186:187], v20, s[8:9] offset:1664
	global_load_dwordx2 v[172:173], v17, s[30:31] offset:2592
	global_load_dwordx2 v[188:189], v20, s[8:9] offset:1792
	global_load_dwordx2 v[174:175], v17, s[30:31] offset:2736
	global_load_dwordx2 v[190:191], v20, s[8:9] offset:1920
	global_load_dwordx4 v[196:199], v21, s[26:27] offset:160
	global_load_dwordx4 v[200:203], v21, s[26:27] offset:176
	global_load_dwordx4 v[204:207], v21, s[40:41] offset:160
	global_load_dwordx4 v[208:211], v21, s[40:41] offset:176
	s_waitcnt vmcnt(40)
	v_mul_f32_e32 v34, v64, v81
	v_mul_f32_e32 v33, v65, v81
	v_fmac_f32_e32 v34, v65, v80
	v_fma_f32 v33, v64, v80, -v33
	v_mul_f32_e32 v34, v104, v34
	v_fma_f32 v33, v96, v33, -v34
	v_add_f32_e32 v32, v32, v33
	v_mul_f32_e32 v36, v66, v83
	v_mul_f32_e32 v35, v67, v83
	v_fmac_f32_e32 v36, v67, v82
	v_fma_f32 v35, v66, v82, -v35
	v_mul_f32_e32 v36, v105, v36
	v_fma_f32 v35, v97, v35, -v36
	v_add_f32_e32 v32, v32, v35
	v_mul_f32_e32 v34, v68, v85
	v_mul_f32_e32 v33, v69, v85
	v_fmac_f32_e32 v34, v69, v84
	v_fma_f32 v33, v68, v84, -v33
	v_mul_f32_e32 v34, v106, v34
	v_fma_f32 v33, v98, v33, -v34
	v_add_f32_e32 v32, v32, v33
	v_mul_f32_e32 v36, v70, v87
	v_mul_f32_e32 v35, v71, v87
	v_fmac_f32_e32 v36, v71, v86
	v_fma_f32 v35, v70, v86, -v35
	v_mul_f32_e32 v36, v107, v36
	v_fma_f32 v35, v99, v35, -v36
	v_add_f32_e32 v32, v32, v35
	v_mul_f32_e32 v34, v72, v89
	v_mul_f32_e32 v33, v73, v89
	v_fmac_f32_e32 v34, v73, v88
	v_fma_f32 v33, v72, v88, -v33
	v_mul_f32_e32 v34, v108, v34
	v_fma_f32 v33, v100, v33, -v34
	v_add_f32_e32 v32, v32, v33
	v_mul_f32_e32 v36, v74, v91
	v_mul_f32_e32 v35, v75, v91
	v_fmac_f32_e32 v36, v75, v90
	v_fma_f32 v35, v74, v90, -v35
	v_mul_f32_e32 v36, v109, v36
	v_fma_f32 v35, v101, v35, -v36
	v_add_f32_e32 v32, v32, v35
	v_mul_f32_e32 v34, v76, v93
	v_mul_f32_e32 v33, v77, v93
	v_fmac_f32_e32 v34, v77, v92
	v_fma_f32 v33, v76, v92, -v33
	v_mul_f32_e32 v34, v110, v34
	v_fma_f32 v33, v102, v33, -v34
	v_add_f32_e32 v32, v32, v33
	v_mul_f32_e32 v36, v78, v95
	v_mul_f32_e32 v35, v79, v95
	v_fmac_f32_e32 v36, v79, v94
	v_fma_f32 v35, v78, v94, -v35
	v_mul_f32_e32 v36, v111, v36
	v_fma_f32 v35, v103, v35, -v36
	v_add_f32_e32 v32, v32, v35
	global_load_dwordx2 v[64:65], v17, s[30:31] offset:2880
	global_load_dwordx2 v[80:81], v20, s[8:9] offset:2048
	global_load_dwordx2 v[66:67], v17, s[30:31] offset:3024
	global_load_dwordx2 v[82:83], v20, s[8:9] offset:2176
	global_load_dwordx2 v[68:69], v17, s[30:31] offset:3168
	global_load_dwordx2 v[84:85], v20, s[8:9] offset:2304
	global_load_dwordx2 v[70:71], v17, s[30:31] offset:3312
	global_load_dwordx2 v[86:87], v20, s[8:9] offset:2432
	global_load_dwordx2 v[72:73], v17, s[30:31] offset:3456
	global_load_dwordx2 v[88:89], v20, s[8:9] offset:2560
	global_load_dwordx2 v[74:75], v17, s[30:31] offset:3600
	global_load_dwordx2 v[90:91], v20, s[8:9] offset:2688
	global_load_dwordx2 v[76:77], v17, s[30:31] offset:3744
	global_load_dwordx2 v[92:93], v20, s[8:9] offset:2816
	global_load_dwordx2 v[78:79], v17, s[30:31] offset:3888
	global_load_dwordx2 v[94:95], v20, s[8:9] offset:2944
	global_load_dwordx4 v[96:99], v21, s[26:27] offset:192
	global_load_dwordx4 v[100:103], v21, s[26:27] offset:208
	global_load_dwordx4 v[104:107], v21, s[40:41] offset:192
	global_load_dwordx4 v[108:111], v21, s[40:41] offset:208
	s_waitcnt vmcnt(40)
; __device__ void s5_stage2(const Params& p, int l) {
;     ...
;     for (int o = t0; o < 524288; o += gs) {
;         const int c2 = o & 15, c = (o >> 4) & 15, k = (o >> 8) & 15, dg = o >> 12;
;         float acc = 0.f;
;         for (int p0 = 0; p0 < 64; p0 += 8) {
;             float2 A[8], Bb[8]; float Cr[8], Ci[8];
; #pragma unroll
;             for (int q = 0; q < 8; ++q) { const int sidx = dg * 64 + p0 + q; A[q] = Apow[sidx * 18 + k]; Bb[q] = Bbar[sidx * 16 + c2]; Cr[q] = cre[(dg * 16 + c) * 64 + p0 + q]; Ci[q] = cim[(dg * 16 + c) * 64 + p0 + q]; }
;             asm volatile("" ::: "memory");
; #pragma unroll
;             for (int q = 0; q < 8; ++q) { const float abr = A[q].x * Bb[q].x - A[q].y * Bb[q].y, abi = A[q].x * Bb[q].y + A[q].y * Bb[q].x; acc += Cr[q] * abr - Ci[q] * abi; }
;         }
;         Kd[o] = acc;
;     }
	v_mul_f32_e32 v34, v112, v129
	v_mul_f32_e32 v33, v113, v129
	v_fmac_f32_e32 v34, v113, v128
	v_fma_f32 v33, v112, v128, -v33
	v_mul_f32_e32 v34, v152, v34
	v_fma_f32 v33, v144, v33, -v34
	v_add_f32_e32 v32, v32, v33
	v_mul_f32_e32 v36, v114, v131
	v_mul_f32_e32 v35, v115, v131
	v_fmac_f32_e32 v36, v115, v130
	v_fma_f32 v35, v114, v130, -v35
	v_mul_f32_e32 v36, v153, v36
	v_fma_f32 v35, v145, v35, -v36
	v_add_f32_e32 v32, v32, v35
	v_mul_f32_e32 v34, v116, v133
	v_mul_f32_e32 v33, v117, v133
	v_fmac_f32_e32 v34, v117, v132
	v_fma_f32 v33, v116, v132, -v33
	v_mul_f32_e32 v34, v154, v34
	v_fma_f32 v33, v146, v33, -v34
	v_add_f32_e32 v32, v32, v33
	v_mul_f32_e32 v36, v118, v135
	v_mul_f32_e32 v35, v119, v135
	v_fmac_f32_e32 v36, v119, v134
	v_fma_f32 v35, v118, v134, -v35
	v_mul_f32_e32 v36, v155, v36
	v_fma_f32 v35, v147, v35, -v36
	v_add_f32_e32 v32, v32, v35
	v_mul_f32_e32 v34, v120, v137
	v_mul_f32_e32 v33, v121, v137
	v_fmac_f32_e32 v34, v121, v136
	v_fma_f32 v33, v120, v136, -v33
	v_mul_f32_e32 v34, v156, v34
	v_fma_f32 v33, v148, v33, -v34
	v_add_f32_e32 v32, v32, v33
	v_mul_f32_e32 v36, v122, v139
	v_mul_f32_e32 v35, v123, v139
	v_fmac_f32_e32 v36, v123, v138
	v_fma_f32 v35, v122, v138, -v35
	v_mul_f32_e32 v36, v157, v36
	v_fma_f32 v35, v149, v35, -v36
	v_add_f32_e32 v32, v32, v35
	v_mul_f32_e32 v34, v124, v141
	v_mul_f32_e32 v33, v125, v141
	v_fmac_f32_e32 v34, v125, v140
	v_fma_f32 v33, v124, v140, -v33
	v_mul_f32_e32 v34, v158, v34
	v_fma_f32 v33, v150, v33, -v34
	v_add_f32_e32 v32, v32, v33
	v_mul_f32_e32 v36, v126, v143
	v_mul_f32_e32 v35, v127, v143
	v_fmac_f32_e32 v36, v127, v142
	v_fma_f32 v35, v126, v142, -v35
	v_mul_f32_e32 v36, v159, v36
	v_fma_f32 v35, v151, v35, -v36
	v_add_f32_e32 v32, v32, v35
	global_load_dwordx2 v[112:113], v18, s[30:31]
	global_load_dwordx2 v[128:129], v20, s[8:9] offset:3072
	global_load_dwordx2 v[114:115], v18, s[30:31] offset:144
	global_load_dwordx2 v[130:131], v20, s[8:9] offset:3200
	global_load_dwordx2 v[116:117], v18, s[30:31] offset:288
	global_load_dwordx2 v[132:133], v20, s[8:9] offset:3328
	global_load_dwordx2 v[118:119], v18, s[30:31] offset:432
	global_load_dwordx2 v[134:135], v20, s[8:9] offset:3456
	global_load_dwordx2 v[120:121], v18, s[30:31] offset:576
	global_load_dwordx2 v[136:137], v20, s[8:9] offset:3584
	global_load_dwordx2 v[122:123], v18, s[30:31] offset:720
	global_load_dwordx2 v[138:139], v20, s[8:9] offset:3712
	global_load_dwordx2 v[124:125], v18, s[30:31] offset:864
	global_load_dwordx2 v[140:141], v20, s[8:9] offset:3840
	global_load_dwordx2 v[126:127], v18, s[30:31] offset:1008
	global_load_dwordx2 v[142:143], v20, s[8:9] offset:3968
	global_load_dwordx4 v[144:147], v21, s[26:27] offset:224
	global_load_dwordx4 v[148:151], v21, s[26:27] offset:240
	global_load_dwordx4 v[152:155], v21, s[40:41] offset:224
	global_load_dwordx4 v[156:159], v21, s[40:41] offset:240
	s_waitcnt vmcnt(40)
	v_mul_f32_e32 v34, v160, v177
	v_mul_f32_e32 v33, v161, v177
	v_fmac_f32_e32 v34, v161, v176
	v_fma_f32 v33, v160, v176, -v33
	v_mul_f32_e32 v34, v204, v34
	v_fma_f32 v33, v196, v33, -v34
	v_add_f32_e32 v32, v32, v33
	v_mul_f32_e32 v36, v162, v179
	v_mul_f32_e32 v35, v163, v179
	v_fmac_f32_e32 v36, v163, v178
	v_fma_f32 v35, v162, v178, -v35
	v_mul_f32_e32 v36, v205, v36
	v_fma_f32 v35, v197, v35, -v36
	v_add_f32_e32 v32, v32, v35
	v_mul_f32_e32 v34, v164, v181
	v_mul_f32_e32 v33, v165, v181
	v_fmac_f32_e32 v34, v165, v180
	v_fma_f32 v33, v164, v180, -v33
	v_mul_f32_e32 v34, v206, v34
	v_fma_f32 v33, v198, v33, -v34
	v_add_f32_e32 v32, v32, v33
	v_mul_f32_e32 v36, v166, v183
	v_mul_f32_e32 v35, v167, v183
	v_fmac_f32_e32 v36, v167, v182
	v_fma_f32 v35, v166, v182, -v35
	v_mul_f32_e32 v36, v207, v36
	v_fma_f32 v35, v199, v35, -v36
	v_add_f32_e32 v32, v32, v35
	v_mul_f32_e32 v34, v168, v185
	v_mul_f32_e32 v33, v169, v185
	v_fmac_f32_e32 v34, v169, v184
	v_fma_f32 v33, v168, v184, -v33
	v_mul_f32_e32 v34, v208, v34
	v_fma_f32 v33, v200, v33, -v34
	v_add_f32_e32 v32, v32, v33
	v_mul_f32_e32 v36, v170, v187
	v_mul_f32_e32 v35, v171, v187
	v_fmac_f32_e32 v36, v171, v186
	v_fma_f32 v35, v170, v186, -v35
	v_mul_f32_e32 v36, v209, v36
	v_fma_f32 v35, v201, v35, -v36
	v_add_f32_e32 v32, v32, v35
	v_mul_f32_e32 v34, v172, v189
	v_mul_f32_e32 v33, v173, v189
	v_fmac_f32_e32 v34, v173, v188
	v_fma_f32 v33, v172, v188, -v33
	v_mul_f32_e32 v34, v210, v34
	v_fma_f32 v33, v202, v33, -v34
	v_add_f32_e32 v32, v32, v33
	v_mul_f32_e32 v36, v174, v191
	v_mul_f32_e32 v35, v175, v191
	v_fmac_f32_e32 v36, v175, v190
	v_fma_f32 v35, v174, v190, -v35
	v_mul_f32_e32 v36, v211, v36
	v_fma_f32 v35, v203, v35, -v36
	v_add_f32_e32 v32, v32, v35
	global_load_dwordx2 v[160:161], v22, s[30:31] offset:2304
	global_load_dwordx2 v[176:177], v25, s[8:9] offset:2048
	global_load_dwordx2 v[162:163], v22, s[30:31] offset:2448
	global_load_dwordx2 v[178:179], v25, s[8:9] offset:2176
	global_load_dwordx2 v[164:165], v22, s[30:31] offset:2592
	global_load_dwordx2 v[180:181], v25, s[8:9] offset:2304
	global_load_dwordx2 v[166:167], v22, s[30:31] offset:2736
	global_load_dwordx2 v[182:183], v25, s[8:9] offset:2432
	global_load_dwordx2 v[168:169], v22, s[30:31] offset:2880
	global_load_dwordx2 v[184:185], v25, s[8:9] offset:2560
	global_load_dwordx2 v[170:171], v22, s[30:31] offset:3024
	global_load_dwordx2 v[186:187], v25, s[8:9] offset:2688
	global_load_dwordx2 v[172:173], v22, s[30:31] offset:3168
	global_load_dwordx2 v[188:189], v25, s[8:9] offset:2816
	global_load_dwordx2 v[174:175], v22, s[30:31] offset:3312
	global_load_dwordx2 v[190:191], v25, s[8:9] offset:2944
	global_load_dwordx4 v[196:199], v27, s[26:27] offset:64
	global_load_dwordx4 v[200:203], v27, s[26:27] offset:80
	global_load_dwordx4 v[204:207], v27, s[40:41] offset:64
	global_load_dwordx4 v[208:211], v27, s[40:41] offset:80
	s_waitcnt vmcnt(40)
; __device__ void s5_stage2(const Params& p, int l) {
;     ...
;     for (int o = t0; o < 524288; o += gs) {
;         const int c2 = o & 15, c = (o >> 4) & 15, k = (o >> 8) & 15, dg = o >> 12;
;         float acc = 0.f;
;         for (int p0 = 0; p0 < 64; p0 += 8) {
;             float2 A[8], Bb[8]; float Cr[8], Ci[8];
; #pragma unroll
;             for (int q = 0; q < 8; ++q) { const int sidx = dg * 64 + p0 + q; A[q] = Apow[sidx * 18 + k]; Bb[q] = Bbar[sidx * 16 + c2]; Cr[q] = cre[(dg * 16 + c) * 64 + p0 + q]; Ci[q] = cim[(dg * 16 + c) * 64 + p0 + q]; }
;             asm volatile("" ::: "memory");
; #pragma unroll
;             for (int q = 0; q < 8; ++q) { const float abr = A[q].x * Bb[q].x - A[q].y * Bb[q].y, abi = A[q].x * Bb[q].y + A[q].y * Bb[q].x; acc += Cr[q] * abr - Ci[q] * abi; }
;         }
;         Kd[o] = acc;
;     }
	v_mul_f32_e32 v34, v64, v81
	v_mul_f32_e32 v33, v65, v81
	v_fmac_f32_e32 v34, v65, v80
	v_fma_f32 v33, v64, v80, -v33
	v_mul_f32_e32 v34, v104, v34
	v_fma_f32 v33, v96, v33, -v34
	v_add_f32_e32 v32, v32, v33
	v_mul_f32_e32 v36, v66, v83
	v_mul_f32_e32 v35, v67, v83
	v_fmac_f32_e32 v36, v67, v82
	v_fma_f32 v35, v66, v82, -v35
	v_mul_f32_e32 v36, v105, v36
	v_fma_f32 v35, v97, v35, -v36
	v_add_f32_e32 v32, v32, v35
	v_mul_f32_e32 v34, v68, v85
	v_mul_f32_e32 v33, v69, v85
	v_fmac_f32_e32 v34, v69, v84
	v_fma_f32 v33, v68, v84, -v33
	v_mul_f32_e32 v34, v106, v34
	v_fma_f32 v33, v98, v33, -v34
	v_add_f32_e32 v32, v32, v33
	v_mul_f32_e32 v36, v70, v87
	v_mul_f32_e32 v35, v71, v87
	v_fmac_f32_e32 v36, v71, v86
	v_fma_f32 v35, v70, v86, -v35
	v_mul_f32_e32 v36, v107, v36
	v_fma_f32 v35, v99, v35, -v36
	v_add_f32_e32 v32, v32, v35
	v_mul_f32_e32 v34, v72, v89
	v_mul_f32_e32 v33, v73, v89
	v_fmac_f32_e32 v34, v73, v88
	v_fma_f32 v33, v72, v88, -v33
	v_mul_f32_e32 v34, v108, v34
	v_fma_f32 v33, v100, v33, -v34
	v_add_f32_e32 v32, v32, v33
	v_mul_f32_e32 v36, v74, v91
	v_mul_f32_e32 v35, v75, v91
	v_fmac_f32_e32 v36, v75, v90
	v_fma_f32 v35, v74, v90, -v35
	v_mul_f32_e32 v36, v109, v36
	v_fma_f32 v35, v101, v35, -v36
	v_add_f32_e32 v32, v32, v35
	v_mul_f32_e32 v34, v76, v93
	v_mul_f32_e32 v33, v77, v93
	v_fmac_f32_e32 v34, v77, v92
	v_fma_f32 v33, v76, v92, -v33
	v_mul_f32_e32 v34, v110, v34
	v_fma_f32 v33, v102, v33, -v34
	v_add_f32_e32 v32, v32, v33
	v_mul_f32_e32 v36, v78, v95
	v_mul_f32_e32 v35, v79, v95
	v_fmac_f32_e32 v36, v79, v94
	v_fma_f32 v35, v78, v94, -v35
	v_mul_f32_e32 v36, v111, v36
	v_fma_f32 v35, v103, v35, -v36
	v_add_f32_e32 v32, v32, v35
	global_load_dwordx2 v[64:65], v22, s[30:31]
	global_load_dwordx2 v[80:81], v25, s[8:9]
	global_load_dwordx2 v[66:67], v22, s[30:31] offset:144
	global_load_dwordx2 v[82:83], v25, s[8:9] offset:128
	global_load_dwordx2 v[68:69], v22, s[30:31] offset:288
	global_load_dwordx2 v[84:85], v25, s[8:9] offset:256
	global_load_dwordx2 v[70:71], v22, s[30:31] offset:432
	global_load_dwordx2 v[86:87], v25, s[8:9] offset:384
	global_load_dwordx2 v[72:73], v22, s[30:31] offset:576
	global_load_dwordx2 v[88:89], v25, s[8:9] offset:512
	global_load_dwordx2 v[74:75], v22, s[30:31] offset:720
	global_load_dwordx2 v[90:91], v25, s[8:9] offset:640
	global_load_dwordx2 v[76:77], v22, s[30:31] offset:864
	global_load_dwordx2 v[92:93], v25, s[8:9] offset:768
	global_load_dwordx2 v[78:79], v22, s[30:31] offset:1008
	global_load_dwordx2 v[94:95], v25, s[8:9] offset:896
	global_load_dwordx4 v[96:99], v27, s[26:27]
	global_load_dwordx4 v[100:103], v27, s[26:27] offset:16
	global_load_dwordx4 v[104:107], v27, s[40:41]
	global_load_dwordx4 v[108:111], v27, s[40:41] offset:16
	s_waitcnt vmcnt(40)
	v_mul_f32_e32 v34, v112, v129
	v_mul_f32_e32 v33, v113, v129
	v_fmac_f32_e32 v34, v113, v128
	v_fma_f32 v33, v112, v128, -v33
	v_mul_f32_e32 v34, v152, v34
	v_fma_f32 v33, v144, v33, -v34
	v_add_f32_e32 v32, v32, v33
	v_mul_f32_e32 v36, v114, v131
	v_mul_f32_e32 v35, v115, v131
	v_fmac_f32_e32 v36, v115, v130
	v_fma_f32 v35, v114, v130, -v35
	v_mul_f32_e32 v36, v153, v36
	v_fma_f32 v35, v145, v35, -v36
	v_add_f32_e32 v32, v32, v35
	v_mul_f32_e32 v34, v116, v133
	v_mul_f32_e32 v33, v117, v133
	v_fmac_f32_e32 v34, v117, v132
	v_fma_f32 v33, v116, v132, -v33
	v_mul_f32_e32 v34, v154, v34
	v_fma_f32 v33, v146, v33, -v34
	v_add_f32_e32 v32, v32, v33
	v_mul_f32_e32 v36, v118, v135
	v_mul_f32_e32 v35, v119, v135
	v_fmac_f32_e32 v36, v119, v134
	v_fma_f32 v35, v118, v134, -v35
	v_mul_f32_e32 v36, v155, v36
	v_fma_f32 v35, v147, v35, -v36
	v_add_f32_e32 v32, v32, v35
	v_mul_f32_e32 v34, v120, v137
	v_mul_f32_e32 v33, v121, v137
	v_fmac_f32_e32 v34, v121, v136
	v_fma_f32 v33, v120, v136, -v33
	v_mul_f32_e32 v34, v156, v34
	v_fma_f32 v33, v148, v33, -v34
	v_add_f32_e32 v32, v32, v33
	v_mul_f32_e32 v36, v122, v139
	v_mul_f32_e32 v35, v123, v139
	v_fmac_f32_e32 v36, v123, v138
	v_fma_f32 v35, v122, v138, -v35
	v_mul_f32_e32 v36, v157, v36
	v_fma_f32 v35, v149, v35, -v36
	v_add_f32_e32 v32, v32, v35
	v_mul_f32_e32 v34, v124, v141
	v_mul_f32_e32 v33, v125, v141
	v_fmac_f32_e32 v34, v125, v140
	v_fma_f32 v33, v124, v140, -v33
	v_mul_f32_e32 v34, v158, v34
	v_fma_f32 v33, v150, v33, -v34
	v_add_f32_e32 v32, v32, v33
	v_mul_f32_e32 v36, v126, v143
	v_mul_f32_e32 v35, v127, v143
	v_fmac_f32_e32 v36, v127, v142
	v_fma_f32 v35, v126, v142, -v35
	v_mul_f32_e32 v36, v159, v36
	v_fma_f32 v35, v151, v35, -v36
	v_add_f32_e32 v32, v32, v35
	global_load_dwordx2 v[112:113], v22, s[30:31] offset:1152
	global_load_dwordx2 v[128:129], v25, s[8:9] offset:1024
	global_load_dwordx2 v[114:115], v22, s[30:31] offset:1296
	global_load_dwordx2 v[130:131], v25, s[8:9] offset:1152
	global_load_dwordx2 v[116:117], v22, s[30:31] offset:1440
	global_load_dwordx2 v[132:133], v25, s[8:9] offset:1280
	global_load_dwordx2 v[118:119], v22, s[30:31] offset:1584
	global_load_dwordx2 v[134:135], v25, s[8:9] offset:1408
	global_load_dwordx2 v[120:121], v22, s[30:31] offset:1728
	global_load_dwordx2 v[136:137], v25, s[8:9] offset:1536
	global_load_dwordx2 v[122:123], v22, s[30:31] offset:1872
	global_load_dwordx2 v[138:139], v25, s[8:9] offset:1664
	global_load_dwordx2 v[124:125], v22, s[30:31] offset:2016
	global_load_dwordx2 v[140:141], v25, s[8:9] offset:1792
	global_load_dwordx2 v[126:127], v22, s[30:31] offset:2160
	global_load_dwordx2 v[142:143], v25, s[8:9] offset:1920
	global_load_dwordx4 v[144:147], v27, s[26:27] offset:32
	global_load_dwordx4 v[148:151], v27, s[26:27] offset:48
	global_load_dwordx4 v[152:155], v27, s[40:41] offset:32
	global_load_dwordx4 v[156:159], v27, s[40:41] offset:48
	v_lshlrev_b32_e32 v28, 2, v14
	global_store_dword v28, v32, s[2:3]
	v_mov_b32_e32 v14, v15
	v_mov_b32_e32 v16, v22
	v_mov_b32_e32 v17, v23
	v_mov_b32_e32 v18, v24
	v_mov_b32_e32 v19, v25
	v_mov_b32_e32 v20, v26
	v_mov_b32_e32 v21, v27
	s_and_b64 vcc, exec, s[38:39]
	s_cbranch_vccnz .Lst2_loop
	s_waitcnt vmcnt(0)
